# E + 40-byte s_nop pad after the attention loop: restores the byte placement the later GEMM loops had in C (code-placement test)
# speedup vs baseline: 1.0024x; 1.0024x over previous
; __device__ __forceinline__ unsigned xb_ld(unsigned* p)              { return __hip_atomic_load(p, __ATOMIC_RELAXED, __HIP_MEMORY_SCOPE_AGENT); }
; __device__ __forceinline__ void xcd_barrier_complete(unsigned* bar, unsigned x, unsigned& nloc, unsigned& nx) {
;     const unsigned G = gridDim.x * gridDim.y * gridDim.z;
;     unsigned sum, cnt, mine, sp = 0u;
;     for (;;) {
;         sum = 0u; cnt = 0u; mine = 0u;
; #pragma unroll
;         for (unsigned j = 0; j < 16; ++j) { const unsigned c = xb_ld(&bar[XB_XCNT(j)]); sum += c; cnt += (c > 0u) ? 1u : 0u; mine = (j == x) ? c : mine; }
;         if (sum == G) break;
;         __builtin_amdgcn_s_sleep(1);
;         if ((++sp & 255u) == 0u) { if (xb_ld(&bar[XB_TMO])) break; if (sp > XB_SPIN_CAP) { atomicAdd(&bar[XB_TMO], 1u); break; } }
;     }
; __device__ __forceinline__ void xcd_barrier(const XcdBarrier& b) {
;     asm volatile("s_waitcnt vmcnt(0)" ::: "memory");
;     __syncthreads();
;     if (threadIdx.x == 0) {
;         unsigned* bar = b.bar;
;         __builtin_amdgcn_s_waitcnt(0);
;         unsigned nloc = b.st[0], nx = b.st[1];
;         if (nloc == 0u) { xcd_barrier_complete(bar, b.x, nloc, nx); b.st[0] = nloc; b.st[1] = nx; }
.LBB0_3772:
	s_nop 0
	s_nop 0
	s_nop 0
	s_nop 0
	s_nop 0
	s_nop 0
	s_nop 0
	s_nop 0
	s_nop 0
	s_nop 0
	s_waitcnt vmcnt(0)
	s_barrier
	s_mov_b64 s[0:1], exec
	v_readlane_b32 s2, v243, 6
	v_readlane_b32 s3, v243, 7
	v_readlane_b32 s68, v243, 54
	s_and_b64 s[2:3], s[0:1], s[2:3]
	v_readlane_b32 s69, v243, 55
	s_mov_b64 exec, s[2:3]
	s_cbranch_execz .LBB0_3824
	s_add_i32 s2, 0, 0x23f20
	v_mov_b32_e32 v0, s2
	s_waitcnt vmcnt(0) expcnt(0) lgkmcnt(0)
	ds_read_b32 v2, v0
	s_add_i32 s2, 0, 0x23f24
	v_mov_b32_e32 v0, s2
	ds_read_b32 v0, v0
	s_waitcnt lgkmcnt(1)
	v_cmp_ne_u32_e32 vcc, 0, v2
	s_cbranch_vccnz .LBB0_3788
	v_readlane_b32 s2, v243, 0
	v_readlane_b32 s3, v243, 1
	s_load_dwordx2 s[6:7], s[2:3], 0x4
	s_add_u32 s2, s82, 0x4200
	s_addc_u32 s3, s83, 0
	s_add_u32 s4, s82, 0x4400
	s_addc_u32 s5, s83, 0
	s_waitcnt lgkmcnt(0)
	s_mul_i32 s33, s6, s87
	s_add_u32 s6, s82, 0x4500
	s_mul_i32 s33, s33, s7
	s_addc_u32 s7, s83, 0
	s_add_u32 s8, s82, 0x4600
	s_addc_u32 s9, s83, 0
	s_add_u32 s10, s82, 0x4700
	s_addc_u32 s11, s83, 0
	s_add_u32 s12, s82, 0x4800
	s_addc_u32 s13, s83, 0
	s_add_u32 s14, s82, 0x4900
	s_addc_u32 s15, s83, 0
	s_add_u32 s16, s82, 0x4a00
	s_addc_u32 s17, s83, 0
	s_add_u32 s18, s82, 0x4b00
	s_addc_u32 s19, s83, 0
	s_add_u32 s20, s82, 0x4c00
	s_addc_u32 s21, s83, 0
	s_add_u32 s22, s82, 0x4d00
	s_addc_u32 s23, s83, 0
	s_add_u32 s24, s82, 0x4e00
	s_addc_u32 s25, s83, 0
	s_add_u32 s26, s82, 0x4f00
	s_addc_u32 s27, s83, 0
	s_add_u32 s28, s82, 0x5000
	s_addc_u32 s29, s83, 0
	s_add_u32 s30, s82, 0x5100
	s_addc_u32 s31, s83, 0
	s_add_u32 s34, s82, 0x5200
	s_addc_u32 s35, s83, 0
	s_add_u32 s36, s82, 0x5300
	s_addc_u32 s37, s83, 0
	s_mov_b32 s44, 1
	v_mov_b32_e32 v16, 0
	s_branch .LBB0_3776
